# V tile of the in-projection: un-swapped MFMA order, accumulators staged transposed, V^T written as 256-byte runs (16 lanes a row) instead of 64 scattered 16-byte pieces per store
# baseline (speedup 1.0000x reference)
.Lip_prdone:
	s_barrier
	s_add_i32 m0, s81, 0
	s_nop 0
	global_load_lds_dwordx4 v240, s[76:77]
	s_add_i32 m0, s81, 4096
	s_nop 0
	global_load_lds_dwordx4 v241, s[76:77]
	s_add_i32 m0, s81, 8192
	s_nop 0
	global_load_lds_dwordx4 v242, s[76:77]
	s_add_i32 m0, s81, 12288
	s_nop 0
	global_load_lds_dwordx4 v243, s[76:77]
	s_add_i32 m0, s81, 16384
	s_nop 0
	global_load_lds_dwordx4 v240, s[78:79]
	s_add_i32 m0, s81, 20480
	s_nop 0
	global_load_lds_dwordx4 v241, s[78:79]
	s_add_i32 m0, s81, 24576
	s_nop 0
	global_load_lds_dwordx4 v242, s[78:79]
	s_add_i32 m0, s81, 28672
	s_nop 0
	global_load_lds_dwordx4 v243, s[78:79]
	s_add_u32 s76, s76, 0x80
	s_addc_u32 s77, s77, 0
	s_add_u32 s78, s78, 0x80
	s_addc_u32 s79, s79, 0
	v_and_b32_e32 v100, 15, v138
	v_bfe_u32 v101, v138, 4, 2
	v_lshrrev_b32_e32 v102, 1, v100
	v_xor_b32_e32 v102, v102, v101
	v_lshlrev_b32_e32 v102, 4, v102
	v_lshrrev_b32_e32 v103, 1, v99
	v_and_b32_e32 v99, 1, v99
	v_lshl_add_u32 v96, v103, 6, v100
	v_lshl_add_u32 v244, v96, 7, v102
	v_xor_b32_e32 v245, 64, v244
	v_lshl_add_u32 v96, v99, 6, v100
	v_lshl_add_u32 v246, v96, 7, v102
	v_add_u32_e32 v246, 0x4000, v246
	v_xor_b32_e32 v247, 64, v246
	v_lshl_add_u32 v96, v103, 6, v100
	s_movk_i32 s0, 0x210
	v_mul_lo_u32 v96, v96, s0
	v_lshlrev_b32_e32 v97, 6, v99
	v_lshl_add_u32 v97, v101, 2, v97
	v_lshl_add_u32 v248, v97, 2, v96
	v_lshl_add_u32 v96, v99, 6, v100
	v_mul_lo_u32 v96, v96, s0
	v_lshlrev_b32_e32 v97, 6, v103
	v_lshl_add_u32 v97, v101, 2, v97
	v_lshl_add_u32 v249, v97, 2, v96
	s_movk_i32 s82, 7
	s_cmp_eq_u32 s42, 3
	s_cbranch_scc1 .Lip_vmain
	s_waitcnt vmcnt(0)
	s_barrier
	ds_read_b128 v[64:67], v244 offset:0
	ds_read_b128 v[80:83], v246 offset:0
	ds_read_b128 v[84:87], v246 offset:2048
	ds_read_b128 v[88:91], v246 offset:4096
	ds_read_b128 v[92:95], v246 offset:6144
	ds_read_b128 v[68:71], v244 offset:2048
	ds_read_b128 v[72:75], v244 offset:4096
	ds_read_b128 v[76:79], v244 offset:6144
	s_waitcnt lgkmcnt(6)
	v_mfma_f32_16x16x32_bf16 v[0:3], v[80:83], v[64:67], 0
	ds_read_b128 v[208:211], v245 offset:0
	s_add_i32 m0, s81, 32768
	s_waitcnt lgkmcnt(6)
	v_mfma_f32_16x16x32_bf16 v[4:7], v[84:87], v[64:67], 0
	ds_read_b128 v[224:227], v247 offset:0
	global_load_lds_dwordx4 v240, s[76:77]
	s_waitcnt lgkmcnt(6)
	v_mfma_f32_16x16x32_bf16 v[8:11], v[88:91], v[64:67], 0
	ds_read_b128 v[228:231], v247 offset:2048
	s_add_i32 m0, s81, 36864
	s_waitcnt lgkmcnt(6)
	v_mfma_f32_16x16x32_bf16 v[12:15], v[92:95], v[64:67], 0
	ds_read_b128 v[232:235], v247 offset:4096
	global_load_lds_dwordx4 v241, s[76:77]
	s_waitcnt lgkmcnt(6)
	v_mfma_f32_16x16x32_bf16 v[16:19], v[80:83], v[68:71], 0
	ds_read_b128 v[236:239], v247 offset:6144
	s_add_i32 m0, s81, 40960
	v_mfma_f32_16x16x32_bf16 v[20:23], v[84:87], v[68:71], 0
	ds_read_b128 v[212:215], v245 offset:2048
	global_load_lds_dwordx4 v242, s[76:77]
	v_mfma_f32_16x16x32_bf16 v[24:27], v[88:91], v[68:71], 0
	ds_read_b128 v[216:219], v245 offset:4096
	s_add_i32 m0, s81, 45056
	v_mfma_f32_16x16x32_bf16 v[28:31], v[92:95], v[68:71], 0
	ds_read_b128 v[220:223], v245 offset:6144
	global_load_lds_dwordx4 v243, s[76:77]
	s_waitcnt lgkmcnt(9)
	v_mfma_f32_16x16x32_bf16 v[32:35], v[80:83], v[72:75], 0
	s_add_i32 m0, s81, 49152
	v_mfma_f32_16x16x32_bf16 v[36:39], v[84:87], v[72:75], 0
	global_load_lds_dwordx4 v240, s[78:79]
	v_mfma_f32_16x16x32_bf16 v[40:43], v[88:91], v[72:75], 0
	s_add_i32 m0, s81, 53248
	v_mfma_f32_16x16x32_bf16 v[44:47], v[92:95], v[72:75], 0
	global_load_lds_dwordx4 v241, s[78:79]
	s_waitcnt lgkmcnt(8)
	v_mfma_f32_16x16x32_bf16 v[48:51], v[80:83], v[76:79], 0
	s_add_i32 m0, s81, 57344
	v_mfma_f32_16x16x32_bf16 v[52:55], v[84:87], v[76:79], 0
	global_load_lds_dwordx4 v242, s[78:79]
	v_mfma_f32_16x16x32_bf16 v[56:59], v[88:91], v[76:79], 0
	s_add_i32 m0, s81, 61440
	v_mfma_f32_16x16x32_bf16 v[60:63], v[92:95], v[76:79], 0
	global_load_lds_dwordx4 v243, s[78:79]
	s_waitcnt lgkmcnt(6)
	v_mfma_f32_16x16x32_bf16 v[0:3], v[224:227], v[208:211], v[0:3]
	s_add_u32 s76, s76, 0x80
	s_addc_u32 s77, s77, 0
	s_waitcnt lgkmcnt(5)
	v_mfma_f32_16x16x32_bf16 v[4:7], v[228:231], v[208:211], v[4:7]
	s_waitcnt lgkmcnt(4)
	v_mfma_f32_16x16x32_bf16 v[8:11], v[232:235], v[208:211], v[8:11]
	s_add_u32 s78, s78, 0x80
	s_addc_u32 s79, s79, 0
	s_waitcnt lgkmcnt(3)
	v_mfma_f32_16x16x32_bf16 v[12:15], v[236:239], v[208:211], v[12:15]
	s_waitcnt lgkmcnt(2)
	v_mfma_f32_16x16x32_bf16 v[16:19], v[224:227], v[212:215], v[16:19]
	v_mfma_f32_16x16x32_bf16 v[20:23], v[228:231], v[212:215], v[20:23]
	v_mfma_f32_16x16x32_bf16 v[24:27], v[232:235], v[212:215], v[24:27]
	v_mfma_f32_16x16x32_bf16 v[28:31], v[236:239], v[212:215], v[28:31]
	s_waitcnt lgkmcnt(1)
	v_mfma_f32_16x16x32_bf16 v[32:35], v[224:227], v[216:219], v[32:35]
	v_mfma_f32_16x16x32_bf16 v[36:39], v[228:231], v[216:219], v[36:39]
	v_mfma_f32_16x16x32_bf16 v[40:43], v[232:235], v[216:219], v[40:43]
	v_mfma_f32_16x16x32_bf16 v[44:47], v[236:239], v[216:219], v[44:47]
	s_waitcnt lgkmcnt(0)
	v_mfma_f32_16x16x32_bf16 v[48:51], v[224:227], v[220:223], v[48:51]
	v_mfma_f32_16x16x32_bf16 v[52:55], v[228:231], v[220:223], v[52:55]
	v_mfma_f32_16x16x32_bf16 v[56:59], v[232:235], v[220:223], v[56:59]
	v_mfma_f32_16x16x32_bf16 v[60:63], v[236:239], v[220:223], v[60:63]
	s_waitcnt vmcnt(0)
	s_barrier
	ds_read_b128 v[64:67], v244 offset:32768
	ds_read_b128 v[80:83], v246 offset:32768
	ds_read_b128 v[84:87], v246 offset:34816
	ds_read_b128 v[88:91], v246 offset:36864
	ds_read_b128 v[92:95], v246 offset:38912
	ds_read_b128 v[68:71], v244 offset:34816
	ds_read_b128 v[72:75], v244 offset:36864
	ds_read_b128 v[76:79], v244 offset:38912
	s_waitcnt lgkmcnt(6)
	v_mfma_f32_16x16x32_bf16 v[0:3], v[80:83], v[64:67], v[0:3]
	ds_read_b128 v[208:211], v245 offset:32768
	s_add_i32 m0, s81, 0
	s_waitcnt lgkmcnt(6)
	v_mfma_f32_16x16x32_bf16 v[4:7], v[84:87], v[64:67], v[4:7]
	ds_read_b128 v[224:227], v247 offset:32768
	global_load_lds_dwordx4 v240, s[76:77]
	s_waitcnt lgkmcnt(6)
	v_mfma_f32_16x16x32_bf16 v[8:11], v[88:91], v[64:67], v[8:11]
	ds_read_b128 v[228:231], v247 offset:34816
	s_add_i32 m0, s81, 4096
	s_waitcnt lgkmcnt(6)
	v_mfma_f32_16x16x32_bf16 v[12:15], v[92:95], v[64:67], v[12:15]
	ds_read_b128 v[232:235], v247 offset:36864
	global_load_lds_dwordx4 v241, s[76:77]
	s_waitcnt lgkmcnt(6)
	v_mfma_f32_16x16x32_bf16 v[16:19], v[80:83], v[68:71], v[16:19]
	ds_read_b128 v[236:239], v247 offset:38912
	s_add_i32 m0, s81, 8192
	v_mfma_f32_16x16x32_bf16 v[20:23], v[84:87], v[68:71], v[20:23]
	ds_read_b128 v[212:215], v245 offset:34816
	global_load_lds_dwordx4 v242, s[76:77]
	v_mfma_f32_16x16x32_bf16 v[24:27], v[88:91], v[68:71], v[24:27]
	ds_read_b128 v[216:219], v245 offset:36864
	s_add_i32 m0, s81, 12288
	v_mfma_f32_16x16x32_bf16 v[28:31], v[92:95], v[68:71], v[28:31]
	ds_read_b128 v[220:223], v245 offset:38912
	global_load_lds_dwordx4 v243, s[76:77]
	s_waitcnt lgkmcnt(9)
	v_mfma_f32_16x16x32_bf16 v[32:35], v[80:83], v[72:75], v[32:35]
	s_add_i32 m0, s81, 16384
	v_mfma_f32_16x16x32_bf16 v[36:39], v[84:87], v[72:75], v[36:39]
	global_load_lds_dwordx4 v240, s[78:79]
	v_mfma_f32_16x16x32_bf16 v[40:43], v[88:91], v[72:75], v[40:43]
	s_add_i32 m0, s81, 20480
	v_mfma_f32_16x16x32_bf16 v[44:47], v[92:95], v[72:75], v[44:47]
	global_load_lds_dwordx4 v241, s[78:79]
	s_waitcnt lgkmcnt(8)
	v_mfma_f32_16x16x32_bf16 v[48:51], v[80:83], v[76:79], v[48:51]
	s_add_i32 m0, s81, 24576
	v_mfma_f32_16x16x32_bf16 v[52:55], v[84:87], v[76:79], v[52:55]
	global_load_lds_dwordx4 v242, s[78:79]
	v_mfma_f32_16x16x32_bf16 v[56:59], v[88:91], v[76:79], v[56:59]
	s_add_i32 m0, s81, 28672
	v_mfma_f32_16x16x32_bf16 v[60:63], v[92:95], v[76:79], v[60:63]
	global_load_lds_dwordx4 v243, s[78:79]
	s_waitcnt lgkmcnt(6)
	v_mfma_f32_16x16x32_bf16 v[0:3], v[224:227], v[208:211], v[0:3]
	s_add_u32 s76, s76, 0x80
	s_addc_u32 s77, s77, 0
	s_waitcnt lgkmcnt(5)
	v_mfma_f32_16x16x32_bf16 v[4:7], v[228:231], v[208:211], v[4:7]
	s_waitcnt lgkmcnt(4)
	v_mfma_f32_16x16x32_bf16 v[8:11], v[232:235], v[208:211], v[8:11]
	s_add_u32 s78, s78, 0x80
	s_addc_u32 s79, s79, 0
	s_waitcnt lgkmcnt(3)
	v_mfma_f32_16x16x32_bf16 v[12:15], v[236:239], v[208:211], v[12:15]
	s_waitcnt lgkmcnt(2)
	v_mfma_f32_16x16x32_bf16 v[16:19], v[224:227], v[212:215], v[16:19]
	v_mfma_f32_16x16x32_bf16 v[20:23], v[228:231], v[212:215], v[20:23]
	v_mfma_f32_16x16x32_bf16 v[24:27], v[232:235], v[212:215], v[24:27]
	v_mfma_f32_16x16x32_bf16 v[28:31], v[236:239], v[212:215], v[28:31]
	s_waitcnt lgkmcnt(1)
	v_mfma_f32_16x16x32_bf16 v[32:35], v[224:227], v[216:219], v[32:35]
	v_mfma_f32_16x16x32_bf16 v[36:39], v[228:231], v[216:219], v[36:39]
	v_mfma_f32_16x16x32_bf16 v[40:43], v[232:235], v[216:219], v[40:43]
	v_mfma_f32_16x16x32_bf16 v[44:47], v[236:239], v[216:219], v[44:47]
	s_waitcnt lgkmcnt(0)
	v_mfma_f32_16x16x32_bf16 v[48:51], v[224:227], v[220:223], v[48:51]
	v_mfma_f32_16x16x32_bf16 v[52:55], v[228:231], v[220:223], v[52:55]
	v_mfma_f32_16x16x32_bf16 v[56:59], v[232:235], v[220:223], v[56:59]
	v_mfma_f32_16x16x32_bf16 v[60:63], v[236:239], v[220:223], v[60:63]
	s_movk_i32 s82, 6
.Lip_loop:
	s_waitcnt vmcnt(0)
	s_barrier
	ds_read_b128 v[64:67], v244 offset:0
	ds_read_b128 v[80:83], v246 offset:0
	ds_read_b128 v[84:87], v246 offset:2048
	ds_read_b128 v[88:91], v246 offset:4096
	ds_read_b128 v[92:95], v246 offset:6144
	ds_read_b128 v[68:71], v244 offset:2048
	ds_read_b128 v[72:75], v244 offset:4096
	ds_read_b128 v[76:79], v244 offset:6144
	s_waitcnt lgkmcnt(6)
	v_mfma_f32_16x16x32_bf16 v[0:3], v[80:83], v[64:67], v[0:3]
	ds_read_b128 v[208:211], v245 offset:0
	s_add_i32 m0, s81, 32768
	s_waitcnt lgkmcnt(6)
	v_mfma_f32_16x16x32_bf16 v[4:7], v[84:87], v[64:67], v[4:7]
	ds_read_b128 v[224:227], v247 offset:0
	global_load_lds_dwordx4 v240, s[76:77]
	s_waitcnt lgkmcnt(6)
	v_mfma_f32_16x16x32_bf16 v[8:11], v[88:91], v[64:67], v[8:11]
	ds_read_b128 v[228:231], v247 offset:2048
	s_add_i32 m0, s81, 36864
	s_waitcnt lgkmcnt(6)
	v_mfma_f32_16x16x32_bf16 v[12:15], v[92:95], v[64:67], v[12:15]
	ds_read_b128 v[232:235], v247 offset:4096
	global_load_lds_dwordx4 v241, s[76:77]
	s_waitcnt lgkmcnt(6)
	v_mfma_f32_16x16x32_bf16 v[16:19], v[80:83], v[68:71], v[16:19]
	ds_read_b128 v[236:239], v247 offset:6144
	s_add_i32 m0, s81, 40960
	v_mfma_f32_16x16x32_bf16 v[20:23], v[84:87], v[68:71], v[20:23]
	ds_read_b128 v[212:215], v245 offset:2048
	global_load_lds_dwordx4 v242, s[76:77]
	v_mfma_f32_16x16x32_bf16 v[24:27], v[88:91], v[68:71], v[24:27]
	ds_read_b128 v[216:219], v245 offset:4096
	s_add_i32 m0, s81, 45056
	v_mfma_f32_16x16x32_bf16 v[28:31], v[92:95], v[68:71], v[28:31]
	ds_read_b128 v[220:223], v245 offset:6144
	global_load_lds_dwordx4 v243, s[76:77]
	s_waitcnt lgkmcnt(9)
	v_mfma_f32_16x16x32_bf16 v[32:35], v[80:83], v[72:75], v[32:35]
	s_add_i32 m0, s81, 49152
	v_mfma_f32_16x16x32_bf16 v[36:39], v[84:87], v[72:75], v[36:39]
	global_load_lds_dwordx4 v240, s[78:79]
	v_mfma_f32_16x16x32_bf16 v[40:43], v[88:91], v[72:75], v[40:43]
	s_add_i32 m0, s81, 53248
	v_mfma_f32_16x16x32_bf16 v[44:47], v[92:95], v[72:75], v[44:47]
	global_load_lds_dwordx4 v241, s[78:79]
	s_waitcnt lgkmcnt(8)
	v_mfma_f32_16x16x32_bf16 v[48:51], v[80:83], v[76:79], v[48:51]
	s_add_i32 m0, s81, 57344
	v_mfma_f32_16x16x32_bf16 v[52:55], v[84:87], v[76:79], v[52:55]
	global_load_lds_dwordx4 v242, s[78:79]
	v_mfma_f32_16x16x32_bf16 v[56:59], v[88:91], v[76:79], v[56:59]
	s_add_i32 m0, s81, 61440
	v_mfma_f32_16x16x32_bf16 v[60:63], v[92:95], v[76:79], v[60:63]
	global_load_lds_dwordx4 v243, s[78:79]
	s_waitcnt lgkmcnt(6)
	v_mfma_f32_16x16x32_bf16 v[0:3], v[224:227], v[208:211], v[0:3]
	s_add_u32 s76, s76, 0x80
	s_addc_u32 s77, s77, 0
	s_waitcnt lgkmcnt(5)
	v_mfma_f32_16x16x32_bf16 v[4:7], v[228:231], v[208:211], v[4:7]
	s_waitcnt lgkmcnt(4)
	v_mfma_f32_16x16x32_bf16 v[8:11], v[232:235], v[208:211], v[8:11]
	s_add_u32 s78, s78, 0x80
	s_addc_u32 s79, s79, 0
	s_waitcnt lgkmcnt(3)
	v_mfma_f32_16x16x32_bf16 v[12:15], v[236:239], v[208:211], v[12:15]
	s_waitcnt lgkmcnt(2)
	v_mfma_f32_16x16x32_bf16 v[16:19], v[224:227], v[212:215], v[16:19]
	v_mfma_f32_16x16x32_bf16 v[20:23], v[228:231], v[212:215], v[20:23]
	v_mfma_f32_16x16x32_bf16 v[24:27], v[232:235], v[212:215], v[24:27]
	v_mfma_f32_16x16x32_bf16 v[28:31], v[236:239], v[212:215], v[28:31]
	s_waitcnt lgkmcnt(1)
	v_mfma_f32_16x16x32_bf16 v[32:35], v[224:227], v[216:219], v[32:35]
	v_mfma_f32_16x16x32_bf16 v[36:39], v[228:231], v[216:219], v[36:39]
	v_mfma_f32_16x16x32_bf16 v[40:43], v[232:235], v[216:219], v[40:43]
	v_mfma_f32_16x16x32_bf16 v[44:47], v[236:239], v[216:219], v[44:47]
	s_waitcnt lgkmcnt(0)
	v_mfma_f32_16x16x32_bf16 v[48:51], v[224:227], v[220:223], v[48:51]
	v_mfma_f32_16x16x32_bf16 v[52:55], v[228:231], v[220:223], v[52:55]
	v_mfma_f32_16x16x32_bf16 v[56:59], v[232:235], v[220:223], v[56:59]
	v_mfma_f32_16x16x32_bf16 v[60:63], v[236:239], v[220:223], v[60:63]
	s_waitcnt vmcnt(0)
	s_barrier
	ds_read_b128 v[64:67], v244 offset:32768
	ds_read_b128 v[80:83], v246 offset:32768
	ds_read_b128 v[84:87], v246 offset:34816
	ds_read_b128 v[88:91], v246 offset:36864
	ds_read_b128 v[92:95], v246 offset:38912
	ds_read_b128 v[68:71], v244 offset:34816
	ds_read_b128 v[72:75], v244 offset:36864
	ds_read_b128 v[76:79], v244 offset:38912
	s_waitcnt lgkmcnt(6)
	v_mfma_f32_16x16x32_bf16 v[0:3], v[80:83], v[64:67], v[0:3]
	ds_read_b128 v[208:211], v245 offset:32768
	s_add_i32 m0, s81, 0
	s_waitcnt lgkmcnt(6)
	v_mfma_f32_16x16x32_bf16 v[4:7], v[84:87], v[64:67], v[4:7]
	ds_read_b128 v[224:227], v247 offset:32768
	global_load_lds_dwordx4 v240, s[76:77]
	s_waitcnt lgkmcnt(6)
	v_mfma_f32_16x16x32_bf16 v[8:11], v[88:91], v[64:67], v[8:11]
	ds_read_b128 v[228:231], v247 offset:34816
	s_add_i32 m0, s81, 4096
	s_waitcnt lgkmcnt(6)
	v_mfma_f32_16x16x32_bf16 v[12:15], v[92:95], v[64:67], v[12:15]
	ds_read_b128 v[232:235], v247 offset:36864
	global_load_lds_dwordx4 v241, s[76:77]
	s_waitcnt lgkmcnt(6)
	v_mfma_f32_16x16x32_bf16 v[16:19], v[80:83], v[68:71], v[16:19]
	ds_read_b128 v[236:239], v247 offset:38912
	s_add_i32 m0, s81, 8192
	v_mfma_f32_16x16x32_bf16 v[20:23], v[84:87], v[68:71], v[20:23]
	ds_read_b128 v[212:215], v245 offset:34816
	global_load_lds_dwordx4 v242, s[76:77]
	v_mfma_f32_16x16x32_bf16 v[24:27], v[88:91], v[68:71], v[24:27]
	ds_read_b128 v[216:219], v245 offset:36864
	s_add_i32 m0, s81, 12288
	v_mfma_f32_16x16x32_bf16 v[28:31], v[92:95], v[68:71], v[28:31]
	ds_read_b128 v[220:223], v245 offset:38912
	global_load_lds_dwordx4 v243, s[76:77]
	s_waitcnt lgkmcnt(9)
	v_mfma_f32_16x16x32_bf16 v[32:35], v[80:83], v[72:75], v[32:35]
	s_add_i32 m0, s81, 16384
	v_mfma_f32_16x16x32_bf16 v[36:39], v[84:87], v[72:75], v[36:39]
	global_load_lds_dwordx4 v240, s[78:79]
	v_mfma_f32_16x16x32_bf16 v[40:43], v[88:91], v[72:75], v[40:43]
	s_add_i32 m0, s81, 20480
	v_mfma_f32_16x16x32_bf16 v[44:47], v[92:95], v[72:75], v[44:47]
	global_load_lds_dwordx4 v241, s[78:79]
	s_waitcnt lgkmcnt(8)
	v_mfma_f32_16x16x32_bf16 v[48:51], v[80:83], v[76:79], v[48:51]
	s_add_i32 m0, s81, 24576
	v_mfma_f32_16x16x32_bf16 v[52:55], v[84:87], v[76:79], v[52:55]
	global_load_lds_dwordx4 v242, s[78:79]
	v_mfma_f32_16x16x32_bf16 v[56:59], v[88:91], v[76:79], v[56:59]
	s_add_i32 m0, s81, 28672
	v_mfma_f32_16x16x32_bf16 v[60:63], v[92:95], v[76:79], v[60:63]
	global_load_lds_dwordx4 v243, s[78:79]
	s_waitcnt lgkmcnt(6)
	v_mfma_f32_16x16x32_bf16 v[0:3], v[224:227], v[208:211], v[0:3]
	s_add_u32 s76, s76, 0x80
	s_addc_u32 s77, s77, 0
	s_waitcnt lgkmcnt(5)
	v_mfma_f32_16x16x32_bf16 v[4:7], v[228:231], v[208:211], v[4:7]
	s_waitcnt lgkmcnt(4)
	v_mfma_f32_16x16x32_bf16 v[8:11], v[232:235], v[208:211], v[8:11]
	s_add_u32 s78, s78, 0x80
	s_addc_u32 s79, s79, 0
	s_waitcnt lgkmcnt(3)
	v_mfma_f32_16x16x32_bf16 v[12:15], v[236:239], v[208:211], v[12:15]
	s_waitcnt lgkmcnt(2)
	v_mfma_f32_16x16x32_bf16 v[16:19], v[224:227], v[212:215], v[16:19]
	v_mfma_f32_16x16x32_bf16 v[20:23], v[228:231], v[212:215], v[20:23]
	v_mfma_f32_16x16x32_bf16 v[24:27], v[232:235], v[212:215], v[24:27]
	v_mfma_f32_16x16x32_bf16 v[28:31], v[236:239], v[212:215], v[28:31]
	s_waitcnt lgkmcnt(1)
	v_mfma_f32_16x16x32_bf16 v[32:35], v[224:227], v[216:219], v[32:35]
	v_mfma_f32_16x16x32_bf16 v[36:39], v[228:231], v[216:219], v[36:39]
	v_mfma_f32_16x16x32_bf16 v[40:43], v[232:235], v[216:219], v[40:43]
	v_mfma_f32_16x16x32_bf16 v[44:47], v[236:239], v[216:219], v[44:47]
	s_waitcnt lgkmcnt(0)
	v_mfma_f32_16x16x32_bf16 v[48:51], v[224:227], v[220:223], v[48:51]
	v_mfma_f32_16x16x32_bf16 v[52:55], v[228:231], v[220:223], v[52:55]
	v_mfma_f32_16x16x32_bf16 v[56:59], v[232:235], v[220:223], v[56:59]
	v_mfma_f32_16x16x32_bf16 v[60:63], v[236:239], v[220:223], v[60:63]
	s_sub_u32 s82, s82, 1
	s_cmp_lg_u32 s82, 0
	s_cbranch_scc1 .Lip_loop
	s_waitcnt vmcnt(0)
	s_barrier
	ds_read_b128 v[64:67], v244 offset:0
	ds_read_b128 v[80:83], v246 offset:0
	ds_read_b128 v[84:87], v246 offset:2048
	ds_read_b128 v[88:91], v246 offset:4096
	ds_read_b128 v[92:95], v246 offset:6144
	ds_read_b128 v[68:71], v244 offset:2048
	ds_read_b128 v[72:75], v244 offset:4096
	ds_read_b128 v[76:79], v244 offset:6144
	s_waitcnt lgkmcnt(6)
	v_mfma_f32_16x16x32_bf16 v[0:3], v[80:83], v[64:67], v[0:3]
	ds_read_b128 v[208:211], v245 offset:0
	s_add_i32 m0, s81, 32768
	s_waitcnt lgkmcnt(6)
	v_mfma_f32_16x16x32_bf16 v[4:7], v[84:87], v[64:67], v[4:7]
	ds_read_b128 v[224:227], v247 offset:0
	global_load_lds_dwordx4 v240, s[76:77]
	s_waitcnt lgkmcnt(6)
	v_mfma_f32_16x16x32_bf16 v[8:11], v[88:91], v[64:67], v[8:11]
	ds_read_b128 v[228:231], v247 offset:2048
	s_add_i32 m0, s81, 36864
	s_waitcnt lgkmcnt(6)
	v_mfma_f32_16x16x32_bf16 v[12:15], v[92:95], v[64:67], v[12:15]
	ds_read_b128 v[232:235], v247 offset:4096
	global_load_lds_dwordx4 v241, s[76:77]
	s_waitcnt lgkmcnt(6)
	v_mfma_f32_16x16x32_bf16 v[16:19], v[80:83], v[68:71], v[16:19]
	ds_read_b128 v[236:239], v247 offset:6144
	s_add_i32 m0, s81, 40960
	v_mfma_f32_16x16x32_bf16 v[20:23], v[84:87], v[68:71], v[20:23]
	ds_read_b128 v[212:215], v245 offset:2048
	global_load_lds_dwordx4 v242, s[76:77]
	v_mfma_f32_16x16x32_bf16 v[24:27], v[88:91], v[68:71], v[24:27]
	ds_read_b128 v[216:219], v245 offset:4096
	s_add_i32 m0, s81, 45056
	v_mfma_f32_16x16x32_bf16 v[28:31], v[92:95], v[68:71], v[28:31]
	ds_read_b128 v[220:223], v245 offset:6144
	global_load_lds_dwordx4 v243, s[76:77]
	s_waitcnt lgkmcnt(9)
	v_mfma_f32_16x16x32_bf16 v[32:35], v[80:83], v[72:75], v[32:35]
	s_add_i32 m0, s81, 49152
	v_mfma_f32_16x16x32_bf16 v[36:39], v[84:87], v[72:75], v[36:39]
	global_load_lds_dwordx4 v240, s[78:79]
	v_mfma_f32_16x16x32_bf16 v[40:43], v[88:91], v[72:75], v[40:43]
	s_add_i32 m0, s81, 53248
	v_mfma_f32_16x16x32_bf16 v[44:47], v[92:95], v[72:75], v[44:47]
	global_load_lds_dwordx4 v241, s[78:79]
	s_waitcnt lgkmcnt(8)
	v_mfma_f32_16x16x32_bf16 v[48:51], v[80:83], v[76:79], v[48:51]
	s_add_i32 m0, s81, 57344
	v_mfma_f32_16x16x32_bf16 v[52:55], v[84:87], v[76:79], v[52:55]
	global_load_lds_dwordx4 v242, s[78:79]
	v_mfma_f32_16x16x32_bf16 v[56:59], v[88:91], v[76:79], v[56:59]
	s_add_i32 m0, s81, 61440
	v_mfma_f32_16x16x32_bf16 v[60:63], v[92:95], v[76:79], v[60:63]
	global_load_lds_dwordx4 v243, s[78:79]
	s_waitcnt lgkmcnt(6)
	v_mfma_f32_16x16x32_bf16 v[0:3], v[224:227], v[208:211], v[0:3]
	s_add_u32 s76, s76, 0x80
	s_addc_u32 s77, s77, 0
	s_waitcnt lgkmcnt(5)
	v_mfma_f32_16x16x32_bf16 v[4:7], v[228:231], v[208:211], v[4:7]
	s_waitcnt lgkmcnt(4)
	v_mfma_f32_16x16x32_bf16 v[8:11], v[232:235], v[208:211], v[8:11]
	s_add_u32 s78, s78, 0x80
	s_addc_u32 s79, s79, 0
	s_waitcnt lgkmcnt(3)
	v_mfma_f32_16x16x32_bf16 v[12:15], v[236:239], v[208:211], v[12:15]
	s_waitcnt lgkmcnt(2)
	v_mfma_f32_16x16x32_bf16 v[16:19], v[224:227], v[212:215], v[16:19]
	v_mfma_f32_16x16x32_bf16 v[20:23], v[228:231], v[212:215], v[20:23]
	v_mfma_f32_16x16x32_bf16 v[24:27], v[232:235], v[212:215], v[24:27]
	v_mfma_f32_16x16x32_bf16 v[28:31], v[236:239], v[212:215], v[28:31]
	s_waitcnt lgkmcnt(1)
	v_mfma_f32_16x16x32_bf16 v[32:35], v[224:227], v[216:219], v[32:35]
	v_mfma_f32_16x16x32_bf16 v[36:39], v[228:231], v[216:219], v[36:39]
	v_mfma_f32_16x16x32_bf16 v[40:43], v[232:235], v[216:219], v[40:43]
	v_mfma_f32_16x16x32_bf16 v[44:47], v[236:239], v[216:219], v[44:47]
	s_waitcnt lgkmcnt(0)
	v_mfma_f32_16x16x32_bf16 v[48:51], v[224:227], v[220:223], v[48:51]
	v_mfma_f32_16x16x32_bf16 v[52:55], v[228:231], v[220:223], v[52:55]
	v_mfma_f32_16x16x32_bf16 v[56:59], v[232:235], v[220:223], v[56:59]
	v_mfma_f32_16x16x32_bf16 v[60:63], v[236:239], v[220:223], v[60:63]
	s_waitcnt vmcnt(0)
	s_barrier
	ds_read_b128 v[64:67], v244 offset:32768
	ds_read_b128 v[80:83], v246 offset:32768
	ds_read_b128 v[84:87], v246 offset:34816
	ds_read_b128 v[88:91], v246 offset:36864
	ds_read_b128 v[92:95], v246 offset:38912
	ds_read_b128 v[68:71], v244 offset:34816
	ds_read_b128 v[72:75], v244 offset:36864
	ds_read_b128 v[76:79], v244 offset:38912
	s_waitcnt lgkmcnt(6)
	v_mfma_f32_16x16x32_bf16 v[0:3], v[80:83], v[64:67], v[0:3]
	ds_read_b128 v[208:211], v245 offset:32768
	s_waitcnt lgkmcnt(6)
	v_mfma_f32_16x16x32_bf16 v[4:7], v[84:87], v[64:67], v[4:7]
	ds_read_b128 v[224:227], v247 offset:32768
	s_waitcnt lgkmcnt(6)
	v_mfma_f32_16x16x32_bf16 v[8:11], v[88:91], v[64:67], v[8:11]
	ds_read_b128 v[228:231], v247 offset:34816
	s_waitcnt lgkmcnt(6)
	v_mfma_f32_16x16x32_bf16 v[12:15], v[92:95], v[64:67], v[12:15]
	ds_read_b128 v[232:235], v247 offset:36864
	s_waitcnt lgkmcnt(6)
	v_mfma_f32_16x16x32_bf16 v[16:19], v[80:83], v[68:71], v[16:19]
	ds_read_b128 v[236:239], v247 offset:38912
	v_mfma_f32_16x16x32_bf16 v[20:23], v[84:87], v[68:71], v[20:23]
	ds_read_b128 v[212:215], v245 offset:34816
	v_mfma_f32_16x16x32_bf16 v[24:27], v[88:91], v[68:71], v[24:27]
	ds_read_b128 v[216:219], v245 offset:36864
	v_mfma_f32_16x16x32_bf16 v[28:31], v[92:95], v[68:71], v[28:31]
	ds_read_b128 v[220:223], v245 offset:38912
	s_waitcnt lgkmcnt(9)
	v_mfma_f32_16x16x32_bf16 v[32:35], v[80:83], v[72:75], v[32:35]
	v_mfma_f32_16x16x32_bf16 v[36:39], v[84:87], v[72:75], v[36:39]
	v_mfma_f32_16x16x32_bf16 v[40:43], v[88:91], v[72:75], v[40:43]
	v_mfma_f32_16x16x32_bf16 v[44:47], v[92:95], v[72:75], v[44:47]
	s_waitcnt lgkmcnt(8)
	v_mfma_f32_16x16x32_bf16 v[48:51], v[80:83], v[76:79], v[48:51]
	v_mfma_f32_16x16x32_bf16 v[52:55], v[84:87], v[76:79], v[52:55]
	v_mfma_f32_16x16x32_bf16 v[56:59], v[88:91], v[76:79], v[56:59]
	v_mfma_f32_16x16x32_bf16 v[60:63], v[92:95], v[76:79], v[60:63]
	s_waitcnt lgkmcnt(6)
	v_mfma_f32_16x16x32_bf16 v[0:3], v[224:227], v[208:211], v[0:3]
	s_waitcnt lgkmcnt(5)
	v_mfma_f32_16x16x32_bf16 v[4:7], v[228:231], v[208:211], v[4:7]
	s_waitcnt lgkmcnt(4)
	v_mfma_f32_16x16x32_bf16 v[8:11], v[232:235], v[208:211], v[8:11]
	s_waitcnt lgkmcnt(3)
	v_mfma_f32_16x16x32_bf16 v[12:15], v[236:239], v[208:211], v[12:15]
	s_waitcnt lgkmcnt(2)
	v_mfma_f32_16x16x32_bf16 v[16:19], v[224:227], v[212:215], v[16:19]
	v_mfma_f32_16x16x32_bf16 v[20:23], v[228:231], v[212:215], v[20:23]
	v_mfma_f32_16x16x32_bf16 v[24:27], v[232:235], v[212:215], v[24:27]
	v_mfma_f32_16x16x32_bf16 v[28:31], v[236:239], v[212:215], v[28:31]
	s_waitcnt lgkmcnt(1)
	v_mfma_f32_16x16x32_bf16 v[32:35], v[224:227], v[216:219], v[32:35]
	v_mfma_f32_16x16x32_bf16 v[36:39], v[228:231], v[216:219], v[36:39]
	v_mfma_f32_16x16x32_bf16 v[40:43], v[232:235], v[216:219], v[40:43]
	v_mfma_f32_16x16x32_bf16 v[44:47], v[236:239], v[216:219], v[44:47]
	s_waitcnt lgkmcnt(0)
	v_mfma_f32_16x16x32_bf16 v[48:51], v[224:227], v[220:223], v[48:51]
	v_mfma_f32_16x16x32_bf16 v[52:55], v[228:231], v[220:223], v[52:55]
	v_mfma_f32_16x16x32_bf16 v[56:59], v[232:235], v[220:223], v[56:59]
	v_mfma_f32_16x16x32_bf16 v[60:63], v[236:239], v[220:223], v[60:63]
	s_branch .Lip_kend
.Lip_vmain:
	s_waitcnt vmcnt(0)
	s_barrier
	ds_read_b128 v[64:67], v244 offset:0
	ds_read_b128 v[80:83], v246 offset:0
	ds_read_b128 v[84:87], v246 offset:2048
	ds_read_b128 v[88:91], v246 offset:4096
	ds_read_b128 v[92:95], v246 offset:6144
	ds_read_b128 v[68:71], v244 offset:2048
	ds_read_b128 v[72:75], v244 offset:4096
	ds_read_b128 v[76:79], v244 offset:6144
	s_waitcnt lgkmcnt(6)
	v_mfma_f32_16x16x32_bf16 v[0:3], v[64:67], v[80:83], 0
	ds_read_b128 v[208:211], v245 offset:0
	s_add_i32 m0, s81, 32768
	s_waitcnt lgkmcnt(6)
	v_mfma_f32_16x16x32_bf16 v[4:7], v[64:67], v[84:87], 0
	ds_read_b128 v[224:227], v247 offset:0
	global_load_lds_dwordx4 v240, s[76:77]
	s_waitcnt lgkmcnt(6)
	v_mfma_f32_16x16x32_bf16 v[8:11], v[64:67], v[88:91], 0
	ds_read_b128 v[228:231], v247 offset:2048
	s_add_i32 m0, s81, 36864
	s_waitcnt lgkmcnt(6)
	v_mfma_f32_16x16x32_bf16 v[12:15], v[64:67], v[92:95], 0
	ds_read_b128 v[232:235], v247 offset:4096
	global_load_lds_dwordx4 v241, s[76:77]
	s_waitcnt lgkmcnt(6)
	v_mfma_f32_16x16x32_bf16 v[16:19], v[68:71], v[80:83], 0
	ds_read_b128 v[236:239], v247 offset:6144
	s_add_i32 m0, s81, 40960
	v_mfma_f32_16x16x32_bf16 v[20:23], v[68:71], v[84:87], 0
	ds_read_b128 v[212:215], v245 offset:2048
	global_load_lds_dwordx4 v242, s[76:77]
	v_mfma_f32_16x16x32_bf16 v[24:27], v[68:71], v[88:91], 0
	ds_read_b128 v[216:219], v245 offset:4096
	s_add_i32 m0, s81, 45056
	v_mfma_f32_16x16x32_bf16 v[28:31], v[68:71], v[92:95], 0
	ds_read_b128 v[220:223], v245 offset:6144
	global_load_lds_dwordx4 v243, s[76:77]
	s_waitcnt lgkmcnt(9)
	v_mfma_f32_16x16x32_bf16 v[32:35], v[72:75], v[80:83], 0
	s_add_i32 m0, s81, 49152
	v_mfma_f32_16x16x32_bf16 v[36:39], v[72:75], v[84:87], 0
	global_load_lds_dwordx4 v240, s[78:79]
	v_mfma_f32_16x16x32_bf16 v[40:43], v[72:75], v[88:91], 0
	s_add_i32 m0, s81, 53248
	v_mfma_f32_16x16x32_bf16 v[44:47], v[72:75], v[92:95], 0
	global_load_lds_dwordx4 v241, s[78:79]
	s_waitcnt lgkmcnt(8)
	v_mfma_f32_16x16x32_bf16 v[48:51], v[76:79], v[80:83], 0
	s_add_i32 m0, s81, 57344
	v_mfma_f32_16x16x32_bf16 v[52:55], v[76:79], v[84:87], 0
	global_load_lds_dwordx4 v242, s[78:79]
	v_mfma_f32_16x16x32_bf16 v[56:59], v[76:79], v[88:91], 0
	s_add_i32 m0, s81, 61440
	v_mfma_f32_16x16x32_bf16 v[60:63], v[76:79], v[92:95], 0
	global_load_lds_dwordx4 v243, s[78:79]
	s_waitcnt lgkmcnt(6)
	v_mfma_f32_16x16x32_bf16 v[0:3], v[208:211], v[224:227], v[0:3]
	s_add_u32 s76, s76, 0x80
	s_addc_u32 s77, s77, 0
	s_waitcnt lgkmcnt(5)
	v_mfma_f32_16x16x32_bf16 v[4:7], v[208:211], v[228:231], v[4:7]
	s_waitcnt lgkmcnt(4)
	v_mfma_f32_16x16x32_bf16 v[8:11], v[208:211], v[232:235], v[8:11]
	s_add_u32 s78, s78, 0x80
	s_addc_u32 s79, s79, 0
	s_waitcnt lgkmcnt(3)
	v_mfma_f32_16x16x32_bf16 v[12:15], v[208:211], v[236:239], v[12:15]
	s_waitcnt lgkmcnt(2)
	v_mfma_f32_16x16x32_bf16 v[16:19], v[212:215], v[224:227], v[16:19]
	v_mfma_f32_16x16x32_bf16 v[20:23], v[212:215], v[228:231], v[20:23]
	v_mfma_f32_16x16x32_bf16 v[24:27], v[212:215], v[232:235], v[24:27]
	v_mfma_f32_16x16x32_bf16 v[28:31], v[212:215], v[236:239], v[28:31]
	s_waitcnt lgkmcnt(1)
	v_mfma_f32_16x16x32_bf16 v[32:35], v[216:219], v[224:227], v[32:35]
	v_mfma_f32_16x16x32_bf16 v[36:39], v[216:219], v[228:231], v[36:39]
	v_mfma_f32_16x16x32_bf16 v[40:43], v[216:219], v[232:235], v[40:43]
	v_mfma_f32_16x16x32_bf16 v[44:47], v[216:219], v[236:239], v[44:47]
	s_waitcnt lgkmcnt(0)
	v_mfma_f32_16x16x32_bf16 v[48:51], v[220:223], v[224:227], v[48:51]
	v_mfma_f32_16x16x32_bf16 v[52:55], v[220:223], v[228:231], v[52:55]
	v_mfma_f32_16x16x32_bf16 v[56:59], v[220:223], v[232:235], v[56:59]
	v_mfma_f32_16x16x32_bf16 v[60:63], v[220:223], v[236:239], v[60:63]
	s_waitcnt vmcnt(0)
	s_barrier
	ds_read_b128 v[64:67], v244 offset:32768
	ds_read_b128 v[80:83], v246 offset:32768
	ds_read_b128 v[84:87], v246 offset:34816
	ds_read_b128 v[88:91], v246 offset:36864
	ds_read_b128 v[92:95], v246 offset:38912
	ds_read_b128 v[68:71], v244 offset:34816
	ds_read_b128 v[72:75], v244 offset:36864
	ds_read_b128 v[76:79], v244 offset:38912
	s_waitcnt lgkmcnt(6)
	v_mfma_f32_16x16x32_bf16 v[0:3], v[64:67], v[80:83], v[0:3]
	ds_read_b128 v[208:211], v245 offset:32768
	s_add_i32 m0, s81, 0
	s_waitcnt lgkmcnt(6)
	v_mfma_f32_16x16x32_bf16 v[4:7], v[64:67], v[84:87], v[4:7]
	ds_read_b128 v[224:227], v247 offset:32768
	global_load_lds_dwordx4 v240, s[76:77]
	s_waitcnt lgkmcnt(6)
	v_mfma_f32_16x16x32_bf16 v[8:11], v[64:67], v[88:91], v[8:11]
	ds_read_b128 v[228:231], v247 offset:34816
	s_add_i32 m0, s81, 4096
	s_waitcnt lgkmcnt(6)
	v_mfma_f32_16x16x32_bf16 v[12:15], v[64:67], v[92:95], v[12:15]
	ds_read_b128 v[232:235], v247 offset:36864
	global_load_lds_dwordx4 v241, s[76:77]
	s_waitcnt lgkmcnt(6)
	v_mfma_f32_16x16x32_bf16 v[16:19], v[68:71], v[80:83], v[16:19]
	ds_read_b128 v[236:239], v247 offset:38912
	s_add_i32 m0, s81, 8192
	v_mfma_f32_16x16x32_bf16 v[20:23], v[68:71], v[84:87], v[20:23]
	ds_read_b128 v[212:215], v245 offset:34816
	global_load_lds_dwordx4 v242, s[76:77]
	v_mfma_f32_16x16x32_bf16 v[24:27], v[68:71], v[88:91], v[24:27]
	ds_read_b128 v[216:219], v245 offset:36864
	s_add_i32 m0, s81, 12288
	v_mfma_f32_16x16x32_bf16 v[28:31], v[68:71], v[92:95], v[28:31]
	ds_read_b128 v[220:223], v245 offset:38912
	global_load_lds_dwordx4 v243, s[76:77]
	s_waitcnt lgkmcnt(9)
	v_mfma_f32_16x16x32_bf16 v[32:35], v[72:75], v[80:83], v[32:35]
	s_add_i32 m0, s81, 16384
	v_mfma_f32_16x16x32_bf16 v[36:39], v[72:75], v[84:87], v[36:39]
	global_load_lds_dwordx4 v240, s[78:79]
	v_mfma_f32_16x16x32_bf16 v[40:43], v[72:75], v[88:91], v[40:43]
	s_add_i32 m0, s81, 20480
	v_mfma_f32_16x16x32_bf16 v[44:47], v[72:75], v[92:95], v[44:47]
	global_load_lds_dwordx4 v241, s[78:79]
	s_waitcnt lgkmcnt(8)
	v_mfma_f32_16x16x32_bf16 v[48:51], v[76:79], v[80:83], v[48:51]
	s_add_i32 m0, s81, 24576
	v_mfma_f32_16x16x32_bf16 v[52:55], v[76:79], v[84:87], v[52:55]
	global_load_lds_dwordx4 v242, s[78:79]
	v_mfma_f32_16x16x32_bf16 v[56:59], v[76:79], v[88:91], v[56:59]
	s_add_i32 m0, s81, 28672
	v_mfma_f32_16x16x32_bf16 v[60:63], v[76:79], v[92:95], v[60:63]
	global_load_lds_dwordx4 v243, s[78:79]
	s_waitcnt lgkmcnt(6)
	v_mfma_f32_16x16x32_bf16 v[0:3], v[208:211], v[224:227], v[0:3]
	s_add_u32 s76, s76, 0x80
	s_addc_u32 s77, s77, 0
	s_waitcnt lgkmcnt(5)
	v_mfma_f32_16x16x32_bf16 v[4:7], v[208:211], v[228:231], v[4:7]
	s_waitcnt lgkmcnt(4)
	v_mfma_f32_16x16x32_bf16 v[8:11], v[208:211], v[232:235], v[8:11]
	s_add_u32 s78, s78, 0x80
	s_addc_u32 s79, s79, 0
	s_waitcnt lgkmcnt(3)
	v_mfma_f32_16x16x32_bf16 v[12:15], v[208:211], v[236:239], v[12:15]
	s_waitcnt lgkmcnt(2)
	v_mfma_f32_16x16x32_bf16 v[16:19], v[212:215], v[224:227], v[16:19]
	v_mfma_f32_16x16x32_bf16 v[20:23], v[212:215], v[228:231], v[20:23]
	v_mfma_f32_16x16x32_bf16 v[24:27], v[212:215], v[232:235], v[24:27]
	v_mfma_f32_16x16x32_bf16 v[28:31], v[212:215], v[236:239], v[28:31]
	s_waitcnt lgkmcnt(1)
	v_mfma_f32_16x16x32_bf16 v[32:35], v[216:219], v[224:227], v[32:35]
	v_mfma_f32_16x16x32_bf16 v[36:39], v[216:219], v[228:231], v[36:39]
	v_mfma_f32_16x16x32_bf16 v[40:43], v[216:219], v[232:235], v[40:43]
	v_mfma_f32_16x16x32_bf16 v[44:47], v[216:219], v[236:239], v[44:47]
	s_waitcnt lgkmcnt(0)
	v_mfma_f32_16x16x32_bf16 v[48:51], v[220:223], v[224:227], v[48:51]
	v_mfma_f32_16x16x32_bf16 v[52:55], v[220:223], v[228:231], v[52:55]
	v_mfma_f32_16x16x32_bf16 v[56:59], v[220:223], v[232:235], v[56:59]
	v_mfma_f32_16x16x32_bf16 v[60:63], v[220:223], v[236:239], v[60:63]
	s_movk_i32 s82, 6
.Lip_vloop:
	s_waitcnt vmcnt(0)
	s_barrier
	ds_read_b128 v[64:67], v244 offset:0
	ds_read_b128 v[80:83], v246 offset:0
	ds_read_b128 v[84:87], v246 offset:2048
	ds_read_b128 v[88:91], v246 offset:4096
	ds_read_b128 v[92:95], v246 offset:6144
	ds_read_b128 v[68:71], v244 offset:2048
	ds_read_b128 v[72:75], v244 offset:4096
	ds_read_b128 v[76:79], v244 offset:6144
	s_waitcnt lgkmcnt(6)
	v_mfma_f32_16x16x32_bf16 v[0:3], v[64:67], v[80:83], v[0:3]
	ds_read_b128 v[208:211], v245 offset:0
	s_add_i32 m0, s81, 32768
	s_waitcnt lgkmcnt(6)
	v_mfma_f32_16x16x32_bf16 v[4:7], v[64:67], v[84:87], v[4:7]
	ds_read_b128 v[224:227], v247 offset:0
	global_load_lds_dwordx4 v240, s[76:77]
	s_waitcnt lgkmcnt(6)
	v_mfma_f32_16x16x32_bf16 v[8:11], v[64:67], v[88:91], v[8:11]
	ds_read_b128 v[228:231], v247 offset:2048
	s_add_i32 m0, s81, 36864
	s_waitcnt lgkmcnt(6)
	v_mfma_f32_16x16x32_bf16 v[12:15], v[64:67], v[92:95], v[12:15]
	ds_read_b128 v[232:235], v247 offset:4096
	global_load_lds_dwordx4 v241, s[76:77]
	s_waitcnt lgkmcnt(6)
	v_mfma_f32_16x16x32_bf16 v[16:19], v[68:71], v[80:83], v[16:19]
	ds_read_b128 v[236:239], v247 offset:6144
	s_add_i32 m0, s81, 40960
	v_mfma_f32_16x16x32_bf16 v[20:23], v[68:71], v[84:87], v[20:23]
	ds_read_b128 v[212:215], v245 offset:2048
	global_load_lds_dwordx4 v242, s[76:77]
	v_mfma_f32_16x16x32_bf16 v[24:27], v[68:71], v[88:91], v[24:27]
	ds_read_b128 v[216:219], v245 offset:4096
	s_add_i32 m0, s81, 45056
	v_mfma_f32_16x16x32_bf16 v[28:31], v[68:71], v[92:95], v[28:31]
	ds_read_b128 v[220:223], v245 offset:6144
	global_load_lds_dwordx4 v243, s[76:77]
	s_waitcnt lgkmcnt(9)
	v_mfma_f32_16x16x32_bf16 v[32:35], v[72:75], v[80:83], v[32:35]
	s_add_i32 m0, s81, 49152
	v_mfma_f32_16x16x32_bf16 v[36:39], v[72:75], v[84:87], v[36:39]
	global_load_lds_dwordx4 v240, s[78:79]
	v_mfma_f32_16x16x32_bf16 v[40:43], v[72:75], v[88:91], v[40:43]
	s_add_i32 m0, s81, 53248
	v_mfma_f32_16x16x32_bf16 v[44:47], v[72:75], v[92:95], v[44:47]
	global_load_lds_dwordx4 v241, s[78:79]
	s_waitcnt lgkmcnt(8)
	v_mfma_f32_16x16x32_bf16 v[48:51], v[76:79], v[80:83], v[48:51]
	s_add_i32 m0, s81, 57344
	v_mfma_f32_16x16x32_bf16 v[52:55], v[76:79], v[84:87], v[52:55]
	global_load_lds_dwordx4 v242, s[78:79]
	v_mfma_f32_16x16x32_bf16 v[56:59], v[76:79], v[88:91], v[56:59]
	s_add_i32 m0, s81, 61440
	v_mfma_f32_16x16x32_bf16 v[60:63], v[76:79], v[92:95], v[60:63]
	global_load_lds_dwordx4 v243, s[78:79]
	s_waitcnt lgkmcnt(6)
	v_mfma_f32_16x16x32_bf16 v[0:3], v[208:211], v[224:227], v[0:3]
	s_add_u32 s76, s76, 0x80
	s_addc_u32 s77, s77, 0
	s_waitcnt lgkmcnt(5)
	v_mfma_f32_16x16x32_bf16 v[4:7], v[208:211], v[228:231], v[4:7]
	s_waitcnt lgkmcnt(4)
	v_mfma_f32_16x16x32_bf16 v[8:11], v[208:211], v[232:235], v[8:11]
	s_add_u32 s78, s78, 0x80
	s_addc_u32 s79, s79, 0
	s_waitcnt lgkmcnt(3)
	v_mfma_f32_16x16x32_bf16 v[12:15], v[208:211], v[236:239], v[12:15]
	s_waitcnt lgkmcnt(2)
	v_mfma_f32_16x16x32_bf16 v[16:19], v[212:215], v[224:227], v[16:19]
	v_mfma_f32_16x16x32_bf16 v[20:23], v[212:215], v[228:231], v[20:23]
	v_mfma_f32_16x16x32_bf16 v[24:27], v[212:215], v[232:235], v[24:27]
	v_mfma_f32_16x16x32_bf16 v[28:31], v[212:215], v[236:239], v[28:31]
	s_waitcnt lgkmcnt(1)
	v_mfma_f32_16x16x32_bf16 v[32:35], v[216:219], v[224:227], v[32:35]
	v_mfma_f32_16x16x32_bf16 v[36:39], v[216:219], v[228:231], v[36:39]
	v_mfma_f32_16x16x32_bf16 v[40:43], v[216:219], v[232:235], v[40:43]
	v_mfma_f32_16x16x32_bf16 v[44:47], v[216:219], v[236:239], v[44:47]
	s_waitcnt lgkmcnt(0)
	v_mfma_f32_16x16x32_bf16 v[48:51], v[220:223], v[224:227], v[48:51]
	v_mfma_f32_16x16x32_bf16 v[52:55], v[220:223], v[228:231], v[52:55]
	v_mfma_f32_16x16x32_bf16 v[56:59], v[220:223], v[232:235], v[56:59]
	v_mfma_f32_16x16x32_bf16 v[60:63], v[220:223], v[236:239], v[60:63]
	s_waitcnt vmcnt(0)
	s_barrier
	ds_read_b128 v[64:67], v244 offset:32768
	ds_read_b128 v[80:83], v246 offset:32768
	ds_read_b128 v[84:87], v246 offset:34816
	ds_read_b128 v[88:91], v246 offset:36864
	ds_read_b128 v[92:95], v246 offset:38912
	ds_read_b128 v[68:71], v244 offset:34816
	ds_read_b128 v[72:75], v244 offset:36864
	ds_read_b128 v[76:79], v244 offset:38912
	s_waitcnt lgkmcnt(6)
	v_mfma_f32_16x16x32_bf16 v[0:3], v[64:67], v[80:83], v[0:3]
	ds_read_b128 v[208:211], v245 offset:32768
	s_add_i32 m0, s81, 0
	s_waitcnt lgkmcnt(6)
	v_mfma_f32_16x16x32_bf16 v[4:7], v[64:67], v[84:87], v[4:7]
	ds_read_b128 v[224:227], v247 offset:32768
	global_load_lds_dwordx4 v240, s[76:77]
	s_waitcnt lgkmcnt(6)
	v_mfma_f32_16x16x32_bf16 v[8:11], v[64:67], v[88:91], v[8:11]
	ds_read_b128 v[228:231], v247 offset:34816
	s_add_i32 m0, s81, 4096
	s_waitcnt lgkmcnt(6)
	v_mfma_f32_16x16x32_bf16 v[12:15], v[64:67], v[92:95], v[12:15]
	ds_read_b128 v[232:235], v247 offset:36864
	global_load_lds_dwordx4 v241, s[76:77]
	s_waitcnt lgkmcnt(6)
	v_mfma_f32_16x16x32_bf16 v[16:19], v[68:71], v[80:83], v[16:19]
	ds_read_b128 v[236:239], v247 offset:38912
	s_add_i32 m0, s81, 8192
	v_mfma_f32_16x16x32_bf16 v[20:23], v[68:71], v[84:87], v[20:23]
	ds_read_b128 v[212:215], v245 offset:34816
	global_load_lds_dwordx4 v242, s[76:77]
	v_mfma_f32_16x16x32_bf16 v[24:27], v[68:71], v[88:91], v[24:27]
	ds_read_b128 v[216:219], v245 offset:36864
	s_add_i32 m0, s81, 12288
	v_mfma_f32_16x16x32_bf16 v[28:31], v[68:71], v[92:95], v[28:31]
	ds_read_b128 v[220:223], v245 offset:38912
	global_load_lds_dwordx4 v243, s[76:77]
	s_waitcnt lgkmcnt(9)
	v_mfma_f32_16x16x32_bf16 v[32:35], v[72:75], v[80:83], v[32:35]
	s_add_i32 m0, s81, 16384
	v_mfma_f32_16x16x32_bf16 v[36:39], v[72:75], v[84:87], v[36:39]
	global_load_lds_dwordx4 v240, s[78:79]
	v_mfma_f32_16x16x32_bf16 v[40:43], v[72:75], v[88:91], v[40:43]
	s_add_i32 m0, s81, 20480
	v_mfma_f32_16x16x32_bf16 v[44:47], v[72:75], v[92:95], v[44:47]
	global_load_lds_dwordx4 v241, s[78:79]
	s_waitcnt lgkmcnt(8)
	v_mfma_f32_16x16x32_bf16 v[48:51], v[76:79], v[80:83], v[48:51]
	s_add_i32 m0, s81, 24576
	v_mfma_f32_16x16x32_bf16 v[52:55], v[76:79], v[84:87], v[52:55]
	global_load_lds_dwordx4 v242, s[78:79]
	v_mfma_f32_16x16x32_bf16 v[56:59], v[76:79], v[88:91], v[56:59]
	s_add_i32 m0, s81, 28672
	v_mfma_f32_16x16x32_bf16 v[60:63], v[76:79], v[92:95], v[60:63]
	global_load_lds_dwordx4 v243, s[78:79]
	s_waitcnt lgkmcnt(6)
	v_mfma_f32_16x16x32_bf16 v[0:3], v[208:211], v[224:227], v[0:3]
	s_add_u32 s76, s76, 0x80
	s_addc_u32 s77, s77, 0
	s_waitcnt lgkmcnt(5)
	v_mfma_f32_16x16x32_bf16 v[4:7], v[208:211], v[228:231], v[4:7]
	s_waitcnt lgkmcnt(4)
	v_mfma_f32_16x16x32_bf16 v[8:11], v[208:211], v[232:235], v[8:11]
	s_add_u32 s78, s78, 0x80
	s_addc_u32 s79, s79, 0
	s_waitcnt lgkmcnt(3)
	v_mfma_f32_16x16x32_bf16 v[12:15], v[208:211], v[236:239], v[12:15]
	s_waitcnt lgkmcnt(2)
	v_mfma_f32_16x16x32_bf16 v[16:19], v[212:215], v[224:227], v[16:19]
	v_mfma_f32_16x16x32_bf16 v[20:23], v[212:215], v[228:231], v[20:23]
	v_mfma_f32_16x16x32_bf16 v[24:27], v[212:215], v[232:235], v[24:27]
	v_mfma_f32_16x16x32_bf16 v[28:31], v[212:215], v[236:239], v[28:31]
	s_waitcnt lgkmcnt(1)
	v_mfma_f32_16x16x32_bf16 v[32:35], v[216:219], v[224:227], v[32:35]
	v_mfma_f32_16x16x32_bf16 v[36:39], v[216:219], v[228:231], v[36:39]
	v_mfma_f32_16x16x32_bf16 v[40:43], v[216:219], v[232:235], v[40:43]
	v_mfma_f32_16x16x32_bf16 v[44:47], v[216:219], v[236:239], v[44:47]
	s_waitcnt lgkmcnt(0)
	v_mfma_f32_16x16x32_bf16 v[48:51], v[220:223], v[224:227], v[48:51]
	v_mfma_f32_16x16x32_bf16 v[52:55], v[220:223], v[228:231], v[52:55]
	v_mfma_f32_16x16x32_bf16 v[56:59], v[220:223], v[232:235], v[56:59]
	v_mfma_f32_16x16x32_bf16 v[60:63], v[220:223], v[236:239], v[60:63]
	s_sub_u32 s82, s82, 1
	s_cmp_lg_u32 s82, 0
	s_cbranch_scc1 .Lip_vloop
	s_waitcnt vmcnt(0)
	s_barrier
	ds_read_b128 v[64:67], v244 offset:0
	ds_read_b128 v[80:83], v246 offset:0
	ds_read_b128 v[84:87], v246 offset:2048
	ds_read_b128 v[88:91], v246 offset:4096
	ds_read_b128 v[92:95], v246 offset:6144
	ds_read_b128 v[68:71], v244 offset:2048
	ds_read_b128 v[72:75], v244 offset:4096
	ds_read_b128 v[76:79], v244 offset:6144
	s_waitcnt lgkmcnt(6)
	v_mfma_f32_16x16x32_bf16 v[0:3], v[64:67], v[80:83], v[0:3]
	ds_read_b128 v[208:211], v245 offset:0
	s_add_i32 m0, s81, 32768
	s_waitcnt lgkmcnt(6)
	v_mfma_f32_16x16x32_bf16 v[4:7], v[64:67], v[84:87], v[4:7]
	ds_read_b128 v[224:227], v247 offset:0
	global_load_lds_dwordx4 v240, s[76:77]
	s_waitcnt lgkmcnt(6)
	v_mfma_f32_16x16x32_bf16 v[8:11], v[64:67], v[88:91], v[8:11]
	ds_read_b128 v[228:231], v247 offset:2048
	s_add_i32 m0, s81, 36864
	s_waitcnt lgkmcnt(6)
	v_mfma_f32_16x16x32_bf16 v[12:15], v[64:67], v[92:95], v[12:15]
	ds_read_b128 v[232:235], v247 offset:4096
	global_load_lds_dwordx4 v241, s[76:77]
	s_waitcnt lgkmcnt(6)
	v_mfma_f32_16x16x32_bf16 v[16:19], v[68:71], v[80:83], v[16:19]
	ds_read_b128 v[236:239], v247 offset:6144
	s_add_i32 m0, s81, 40960
	v_mfma_f32_16x16x32_bf16 v[20:23], v[68:71], v[84:87], v[20:23]
	ds_read_b128 v[212:215], v245 offset:2048
	global_load_lds_dwordx4 v242, s[76:77]
	v_mfma_f32_16x16x32_bf16 v[24:27], v[68:71], v[88:91], v[24:27]
	ds_read_b128 v[216:219], v245 offset:4096
	s_add_i32 m0, s81, 45056
	v_mfma_f32_16x16x32_bf16 v[28:31], v[68:71], v[92:95], v[28:31]
	ds_read_b128 v[220:223], v245 offset:6144
	global_load_lds_dwordx4 v243, s[76:77]
	s_waitcnt lgkmcnt(9)
	v_mfma_f32_16x16x32_bf16 v[32:35], v[72:75], v[80:83], v[32:35]
	s_add_i32 m0, s81, 49152
	v_mfma_f32_16x16x32_bf16 v[36:39], v[72:75], v[84:87], v[36:39]
	global_load_lds_dwordx4 v240, s[78:79]
	v_mfma_f32_16x16x32_bf16 v[40:43], v[72:75], v[88:91], v[40:43]
	s_add_i32 m0, s81, 53248
	v_mfma_f32_16x16x32_bf16 v[44:47], v[72:75], v[92:95], v[44:47]
	global_load_lds_dwordx4 v241, s[78:79]
	s_waitcnt lgkmcnt(8)
	v_mfma_f32_16x16x32_bf16 v[48:51], v[76:79], v[80:83], v[48:51]
	s_add_i32 m0, s81, 57344
	v_mfma_f32_16x16x32_bf16 v[52:55], v[76:79], v[84:87], v[52:55]
	global_load_lds_dwordx4 v242, s[78:79]
	v_mfma_f32_16x16x32_bf16 v[56:59], v[76:79], v[88:91], v[56:59]
	s_add_i32 m0, s81, 61440
	v_mfma_f32_16x16x32_bf16 v[60:63], v[76:79], v[92:95], v[60:63]
	global_load_lds_dwordx4 v243, s[78:79]
	s_waitcnt lgkmcnt(6)
	v_mfma_f32_16x16x32_bf16 v[0:3], v[208:211], v[224:227], v[0:3]
	s_add_u32 s76, s76, 0x80
	s_addc_u32 s77, s77, 0
	s_waitcnt lgkmcnt(5)
	v_mfma_f32_16x16x32_bf16 v[4:7], v[208:211], v[228:231], v[4:7]
	s_waitcnt lgkmcnt(4)
	v_mfma_f32_16x16x32_bf16 v[8:11], v[208:211], v[232:235], v[8:11]
	s_add_u32 s78, s78, 0x80
	s_addc_u32 s79, s79, 0
	s_waitcnt lgkmcnt(3)
	v_mfma_f32_16x16x32_bf16 v[12:15], v[208:211], v[236:239], v[12:15]
	s_waitcnt lgkmcnt(2)
	v_mfma_f32_16x16x32_bf16 v[16:19], v[212:215], v[224:227], v[16:19]
	v_mfma_f32_16x16x32_bf16 v[20:23], v[212:215], v[228:231], v[20:23]
	v_mfma_f32_16x16x32_bf16 v[24:27], v[212:215], v[232:235], v[24:27]
	v_mfma_f32_16x16x32_bf16 v[28:31], v[212:215], v[236:239], v[28:31]
	s_waitcnt lgkmcnt(1)
	v_mfma_f32_16x16x32_bf16 v[32:35], v[216:219], v[224:227], v[32:35]
	v_mfma_f32_16x16x32_bf16 v[36:39], v[216:219], v[228:231], v[36:39]
	v_mfma_f32_16x16x32_bf16 v[40:43], v[216:219], v[232:235], v[40:43]
	v_mfma_f32_16x16x32_bf16 v[44:47], v[216:219], v[236:239], v[44:47]
	s_waitcnt lgkmcnt(0)
	v_mfma_f32_16x16x32_bf16 v[48:51], v[220:223], v[224:227], v[48:51]
	v_mfma_f32_16x16x32_bf16 v[52:55], v[220:223], v[228:231], v[52:55]
	v_mfma_f32_16x16x32_bf16 v[56:59], v[220:223], v[232:235], v[56:59]
	v_mfma_f32_16x16x32_bf16 v[60:63], v[220:223], v[236:239], v[60:63]
	s_waitcnt vmcnt(0)
	s_barrier
	ds_read_b128 v[64:67], v244 offset:32768
	ds_read_b128 v[80:83], v246 offset:32768
	ds_read_b128 v[84:87], v246 offset:34816
	ds_read_b128 v[88:91], v246 offset:36864
	ds_read_b128 v[92:95], v246 offset:38912
	ds_read_b128 v[68:71], v244 offset:34816
	ds_read_b128 v[72:75], v244 offset:36864
	ds_read_b128 v[76:79], v244 offset:38912
	s_waitcnt lgkmcnt(6)
	v_mfma_f32_16x16x32_bf16 v[0:3], v[64:67], v[80:83], v[0:3]
	ds_read_b128 v[208:211], v245 offset:32768
	s_waitcnt lgkmcnt(6)
	v_mfma_f32_16x16x32_bf16 v[4:7], v[64:67], v[84:87], v[4:7]
	ds_read_b128 v[224:227], v247 offset:32768
	s_waitcnt lgkmcnt(6)
	v_mfma_f32_16x16x32_bf16 v[8:11], v[64:67], v[88:91], v[8:11]
	ds_read_b128 v[228:231], v247 offset:34816
	s_waitcnt lgkmcnt(6)
	v_mfma_f32_16x16x32_bf16 v[12:15], v[64:67], v[92:95], v[12:15]
	ds_read_b128 v[232:235], v247 offset:36864
	s_waitcnt lgkmcnt(6)
	v_mfma_f32_16x16x32_bf16 v[16:19], v[68:71], v[80:83], v[16:19]
	ds_read_b128 v[236:239], v247 offset:38912
	v_mfma_f32_16x16x32_bf16 v[20:23], v[68:71], v[84:87], v[20:23]
	ds_read_b128 v[212:215], v245 offset:34816
	v_mfma_f32_16x16x32_bf16 v[24:27], v[68:71], v[88:91], v[24:27]
	ds_read_b128 v[216:219], v245 offset:36864
	v_mfma_f32_16x16x32_bf16 v[28:31], v[68:71], v[92:95], v[28:31]
	ds_read_b128 v[220:223], v245 offset:38912
	s_waitcnt lgkmcnt(9)
	v_mfma_f32_16x16x32_bf16 v[32:35], v[72:75], v[80:83], v[32:35]
	v_mfma_f32_16x16x32_bf16 v[36:39], v[72:75], v[84:87], v[36:39]
	v_mfma_f32_16x16x32_bf16 v[40:43], v[72:75], v[88:91], v[40:43]
	v_mfma_f32_16x16x32_bf16 v[44:47], v[72:75], v[92:95], v[44:47]
	s_waitcnt lgkmcnt(8)
	v_mfma_f32_16x16x32_bf16 v[48:51], v[76:79], v[80:83], v[48:51]
	v_mfma_f32_16x16x32_bf16 v[52:55], v[76:79], v[84:87], v[52:55]
	v_mfma_f32_16x16x32_bf16 v[56:59], v[76:79], v[88:91], v[56:59]
	v_mfma_f32_16x16x32_bf16 v[60:63], v[76:79], v[92:95], v[60:63]
	s_waitcnt lgkmcnt(6)
	v_mfma_f32_16x16x32_bf16 v[0:3], v[208:211], v[224:227], v[0:3]
	s_waitcnt lgkmcnt(5)
	v_mfma_f32_16x16x32_bf16 v[4:7], v[208:211], v[228:231], v[4:7]
	s_waitcnt lgkmcnt(4)
	v_mfma_f32_16x16x32_bf16 v[8:11], v[208:211], v[232:235], v[8:11]
	s_waitcnt lgkmcnt(3)
	v_mfma_f32_16x16x32_bf16 v[12:15], v[208:211], v[236:239], v[12:15]
	s_waitcnt lgkmcnt(2)
	v_mfma_f32_16x16x32_bf16 v[16:19], v[212:215], v[224:227], v[16:19]
	v_mfma_f32_16x16x32_bf16 v[20:23], v[212:215], v[228:231], v[20:23]
	v_mfma_f32_16x16x32_bf16 v[24:27], v[212:215], v[232:235], v[24:27]
	v_mfma_f32_16x16x32_bf16 v[28:31], v[212:215], v[236:239], v[28:31]
	s_waitcnt lgkmcnt(1)
	v_mfma_f32_16x16x32_bf16 v[32:35], v[216:219], v[224:227], v[32:35]
	v_mfma_f32_16x16x32_bf16 v[36:39], v[216:219], v[228:231], v[36:39]
	v_mfma_f32_16x16x32_bf16 v[40:43], v[216:219], v[232:235], v[40:43]
	v_mfma_f32_16x16x32_bf16 v[44:47], v[216:219], v[236:239], v[44:47]
	s_waitcnt lgkmcnt(0)
	v_mfma_f32_16x16x32_bf16 v[48:51], v[220:223], v[224:227], v[48:51]
	v_mfma_f32_16x16x32_bf16 v[52:55], v[220:223], v[228:231], v[52:55]
	v_mfma_f32_16x16x32_bf16 v[56:59], v[220:223], v[232:235], v[56:59]
	v_mfma_f32_16x16x32_bf16 v[60:63], v[220:223], v[236:239], v[60:63]
.Lip_kend:
	s_barrier
	s_cmp_eq_u32 s42, 3
	s_cbranch_scc0 .Lip_stgrow
	ds_write_b128 v249, v[0:3] offset:0
	ds_write_b128 v249, v[4:7] offset:8448
	ds_write_b128 v249, v[8:11] offset:16896
	ds_write_b128 v249, v[12:15] offset:25344
	ds_write_b128 v249, v[16:19] offset:64
	ds_write_b128 v249, v[20:23] offset:8512
	ds_write_b128 v249, v[24:27] offset:16960
	ds_write_b128 v249, v[28:31] offset:25408
	ds_write_b128 v249, v[32:35] offset:128
	ds_write_b128 v249, v[36:39] offset:8576
	ds_write_b128 v249, v[40:43] offset:17024
	ds_write_b128 v249, v[44:47] offset:25472
	ds_write_b128 v249, v[48:51] offset:192
	ds_write_b128 v249, v[52:55] offset:8640
	ds_write_b128 v249, v[56:59] offset:17088
	ds_write_b128 v249, v[60:63] offset:25536
	s_branch .Lip_stgdone
.Lip_stgrow:
	ds_write_b128 v248, v[0:3] offset:0
	ds_write_b128 v248, v[4:7] offset:64
	ds_write_b128 v248, v[8:11] offset:128
	ds_write_b128 v248, v[12:15] offset:192
	ds_write_b128 v248, v[16:19] offset:8448
	ds_write_b128 v248, v[20:23] offset:8512
	ds_write_b128 v248, v[24:27] offset:8576
	ds_write_b128 v248, v[28:31] offset:8640
	ds_write_b128 v248, v[32:35] offset:16896
	ds_write_b128 v248, v[36:39] offset:16960
	ds_write_b128 v248, v[40:43] offset:17024
	ds_write_b128 v248, v[44:47] offset:17088
	ds_write_b128 v248, v[48:51] offset:25344
	ds_write_b128 v248, v[52:55] offset:25408
	ds_write_b128 v248, v[56:59] offset:25472
	ds_write_b128 v248, v[60:63] offset:25536
.Lip_stgdone:
	v_mov_b32_e32 v26, v138
	s_lshl_b32 s57, s18, 7
	s_cmpk_lt_u32 s18, 0x80
	s_cselect_b64 s[16:17], -1, 0
	s_mov_b64 s[0:1], -1
	s_mov_b32 s2, 0x40000
	s_cmp_gt_u32 s42, 2
	s_waitcnt lgkmcnt(0)
	s_barrier
	s_cbranch_scc0 .LBB0_270
	s_cmp_lg_u32 s42, 3
	s_cbranch_scc0 .LBB0_272
	s_add_i32 s0, s42, -10
	s_cmp_gt_u32 s0, 7
	s_mov_b64 s[0:1], -1
	s_cbranch_scc0 .LBB0_251
	s_lshl_b32 s0, s42, 7
	s_cmp_lt_u32 s42, 10
	s_movk_i32 s1, 0xfe00
	s_cselect_b32 s1, s1, 0xfffffc00
	s_add_i32 s0, s1, s0
	s_mov_b32 s1, s19
	v_lshlrev_b32_e32 v0, 3, v26
	s_lshl_b64 s[0:1], s[0:1], 1
	v_readlane_b32 s2, v206, 43
	v_and_b32_e32 v1, 0x78, v0
	v_readlane_b32 s3, v206, 44
	s_add_u32 s0, s2, s0
	s_addc_u32 s1, s3, s1
	v_lshlrev_b32_e32 v134, 1, v1
	v_lshlrev_b32_e32 v0, 2, v1
	v_lshl_add_u64 v[2:3], s[0:1], 0, v[134:135]
	s_mov_b32 s0, 0

.LBB0_277:
	v_lshrrev_b32_e32 v64, 4, v26
	v_and_b32_e32 v65, 15, v26
	s_lshl_b32 s0, s2, 7
	v_add_u32_e32 v66, s0, v64
	s_movk_i32 s0, 0x4200
	v_mul_lo_u32 v66, v66, s0
	v_lshl_add_u32 v68, v65, 3, s18
	v_lshl_add_u32 v66, v68, 1, v66
	s_movk_i32 s0, 0x210
	v_mul_lo_u32 v67, v64, s0
	v_lshl_add_u32 v67, v65, 5, v67
	ds_read_b128 v[0:3], v67 offset:0
	ds_read_b128 v[4:7], v67 offset:16
	ds_read_b128 v[8:11], v67 offset:8448
	ds_read_b128 v[12:15], v67 offset:8464
	ds_read_b128 v[16:19], v67 offset:16896
	ds_read_b128 v[20:23], v67 offset:16912
	ds_read_b128 v[24:27], v67 offset:25344
	ds_read_b128 v[28:31], v67 offset:25360
	ds_read_b128 v[32:35], v67 offset:33792
	ds_read_b128 v[36:39], v67 offset:33808
	ds_read_b128 v[40:43], v67 offset:42240
	ds_read_b128 v[44:47], v67 offset:42256
	ds_read_b128 v[48:51], v67 offset:50688
	ds_read_b128 v[52:55], v67 offset:50704
	ds_read_b128 v[56:59], v67 offset:59136
	ds_read_b128 v[60:63], v67 offset:59152
	s_waitcnt lgkmcnt(14)
	v_cvt_pk_bf16_f32 v0, v0, v1
	v_cvt_pk_bf16_f32 v1, v2, v3
	v_cvt_pk_bf16_f32 v2, v4, v5
	v_cvt_pk_bf16_f32 v3, v6, v7
	global_store_dwordx4 v66, v[0:3], s[44:45]
	s_waitcnt lgkmcnt(12)
	v_cvt_pk_bf16_f32 v8, v8, v9
	v_cvt_pk_bf16_f32 v9, v10, v11
	v_cvt_pk_bf16_f32 v10, v12, v13
	v_cvt_pk_bf16_f32 v11, v14, v15
	v_add_u32_e32 v66, 0x42000, v66
	global_store_dwordx4 v66, v[8:11], s[44:45]
	s_waitcnt lgkmcnt(10)
	v_cvt_pk_bf16_f32 v16, v16, v17
	v_cvt_pk_bf16_f32 v17, v18, v19
	v_cvt_pk_bf16_f32 v18, v20, v21
	v_cvt_pk_bf16_f32 v19, v22, v23
	v_add_u32_e32 v66, 0x42000, v66
	global_store_dwordx4 v66, v[16:19], s[44:45]
	s_waitcnt lgkmcnt(8)
	v_cvt_pk_bf16_f32 v24, v24, v25
	v_cvt_pk_bf16_f32 v25, v26, v27
	v_cvt_pk_bf16_f32 v26, v28, v29
	v_cvt_pk_bf16_f32 v27, v30, v31
	v_add_u32_e32 v66, 0x42000, v66
	global_store_dwordx4 v66, v[24:27], s[44:45]
	s_waitcnt lgkmcnt(6)
	v_cvt_pk_bf16_f32 v32, v32, v33
	v_cvt_pk_bf16_f32 v33, v34, v35
	v_cvt_pk_bf16_f32 v34, v36, v37
	v_cvt_pk_bf16_f32 v35, v38, v39
	v_add_u32_e32 v66, 0x42000, v66
	global_store_dwordx4 v66, v[32:35], s[44:45]
	s_waitcnt lgkmcnt(4)
	v_cvt_pk_bf16_f32 v40, v40, v41
	v_cvt_pk_bf16_f32 v41, v42, v43
	v_cvt_pk_bf16_f32 v42, v44, v45
	v_cvt_pk_bf16_f32 v43, v46, v47
	v_add_u32_e32 v66, 0x42000, v66
	global_store_dwordx4 v66, v[40:43], s[44:45]
	s_waitcnt lgkmcnt(2)
	v_cvt_pk_bf16_f32 v48, v48, v49
	v_cvt_pk_bf16_f32 v49, v50, v51
	v_cvt_pk_bf16_f32 v50, v52, v53
	v_cvt_pk_bf16_f32 v51, v54, v55
	v_add_u32_e32 v66, 0x42000, v66
	global_store_dwordx4 v66, v[48:51], s[44:45]
	s_waitcnt lgkmcnt(0)
	v_cvt_pk_bf16_f32 v56, v56, v57
	v_cvt_pk_bf16_f32 v57, v58, v59
	v_cvt_pk_bf16_f32 v58, v60, v61
	v_cvt_pk_bf16_f32 v59, v62, v63
	v_add_u32_e32 v66, 0x42000, v66
	global_store_dwordx4 v66, v[56:59], s[44:45]
